# GEMM accumulator zeroing with v_mov_b64 (64 instead of 128 VALU per unit)
# baseline (speedup 1.0000x reference)
; template <class Epi, class Sched, bool ALIGN_EPI = false, bool SP2 = false>
; __device__ __forceinline__ void gemm_phase(PG8_LAS unsigned char* lds, const Gemm g, const Sched& S, const Epi& E) {
;     ...
; #pragma unroll
;         for (int a = 0; a < 2; ++a)
; #pragma unroll
;             for (int b = 0; b < 2; ++b)
; #pragma unroll
;                 for (int m = 0; m < 4; ++m)
; #pragma unroll
;                     for (int n = 0; n < 2; ++n) acc[a][b][m][n] = (f32x4){0.f, 0.f, 0.f, 0.f};
.LBB0_191:
	s_ashr_i32 s15, s14, 31
	s_lshl_b64 s[16:17], s[14:15], 19
	v_readlane_b32 s18, v235, 31
	v_readlane_b32 s19, v235, 32
	s_add_u32 s16, s18, s16
	s_addc_u32 s17, s19, s17
	s_and_b64 s[18:19], s[0:1], exec
	s_cselect_b32 s15, s17, s23
	s_cselect_b32 s50, s16, s22
	s_ashr_i32 s9, s8, 31
	s_lshl_b64 s[18:19], s[8:9], 19
	s_add_u32 s18, s33, s18
	s_addc_u32 s19, s34, s19
	s_and_b64 s[30:31], s[0:1], exec
	s_cselect_b32 s9, s19, s25
	s_cselect_b32 s51, s18, s24
	s_add_u32 s22, s22, 0x40080
	s_addc_u32 s23, s23, 0
	s_add_u32 s52, s24, 0x100
	v_mov_b32_e32 v0, 0
	s_addc_u32 s53, s25, 0
	s_mov_b32 s54, -2
	v_mov_b32_e32 v1, v0
	v_mov_b64_e32 v[2:3], 0
	v_mov_b64_e32 v[4:5], 0
	v_mov_b64_e32 v[6:7], 0
	v_mov_b64_e32 v[16:17], 0
	v_mov_b64_e32 v[18:19], 0
	v_mov_b64_e32 v[20:21], 0
	v_mov_b64_e32 v[22:23], 0
	v_mov_b64_e32 v[32:33], 0
	v_mov_b64_e32 v[34:35], 0
	v_mov_b64_e32 v[36:37], 0
	v_mov_b64_e32 v[38:39], 0
	v_mov_b64_e32 v[48:49], 0
	v_mov_b64_e32 v[50:51], 0
	v_mov_b64_e32 v[52:53], 0
	v_mov_b64_e32 v[54:55], 0
	v_mov_b64_e32 v[8:9], 0
	v_mov_b64_e32 v[10:11], 0
	v_mov_b64_e32 v[12:13], 0
	v_mov_b64_e32 v[14:15], 0
	v_mov_b64_e32 v[24:25], 0
	v_mov_b64_e32 v[26:27], 0
	v_mov_b64_e32 v[28:29], 0
	v_mov_b64_e32 v[30:31], 0
	v_mov_b64_e32 v[40:41], 0
	v_mov_b64_e32 v[42:43], 0
	v_mov_b64_e32 v[44:45], 0
	v_mov_b64_e32 v[46:47], 0
	v_mov_b64_e32 v[56:57], 0
	v_mov_b64_e32 v[58:59], 0
	v_mov_b64_e32 v[60:61], 0
	v_mov_b64_e32 v[62:63], 0
	v_mov_b64_e32 v[64:65], 0
	v_mov_b64_e32 v[66:67], 0
	v_mov_b64_e32 v[68:69], 0
	v_mov_b64_e32 v[70:71], 0
	v_mov_b64_e32 v[80:81], 0
	v_mov_b64_e32 v[82:83], 0
	v_mov_b64_e32 v[84:85], 0
	v_mov_b64_e32 v[86:87], 0
	v_mov_b64_e32 v[96:97], 0
	v_mov_b64_e32 v[98:99], 0
	v_mov_b64_e32 v[100:101], 0
	v_mov_b64_e32 v[102:103], 0
	v_mov_b64_e32 v[112:113], 0
	v_mov_b64_e32 v[114:115], 0
	v_mov_b64_e32 v[116:117], 0
	v_mov_b64_e32 v[118:119], 0
	v_mov_b64_e32 v[72:73], 0
	v_mov_b64_e32 v[74:75], 0
	v_mov_b64_e32 v[76:77], 0
	v_mov_b64_e32 v[78:79], 0
	v_mov_b64_e32 v[88:89], 0
	v_mov_b64_e32 v[90:91], 0
	v_mov_b64_e32 v[92:93], 0
	v_mov_b64_e32 v[94:95], 0
	v_mov_b64_e32 v[104:105], 0
	v_mov_b64_e32 v[106:107], 0
	v_mov_b64_e32 v[108:109], 0
	v_mov_b64_e32 v[110:111], 0
	v_mov_b64_e32 v[120:121], 0
	v_mov_b64_e32 v[122:123], 0
	v_mov_b64_e32 v[124:125], 0
	v_mov_b64_e32 v[126:127], 0

; template <class Epi, class Sched, bool ALIGN_EPI = false, bool SP2 = false>
; __device__ __forceinline__ void gemm_phase(PG8_LAS unsigned char* lds, const Gemm g, const Sched& S, const Epi& E) {
;     ...
; #pragma unroll
;         for (int a = 0; a < 2; ++a)
; #pragma unroll
;             for (int b = 0; b < 2; ++b)
; #pragma unroll
;                 for (int m = 0; m < 4; ++m)
; #pragma unroll
;                     for (int n = 0; n < 2; ++n) acc[a][b][m][n] = (f32x4){0.f, 0.f, 0.f, 0.f};
.LBB0_273:
	s_add_u32 s58, s34, 0x100
	v_mov_b32_e32 v0, 0
	s_addc_u32 s59, s35, 0
	s_mov_b32 s60, -2
	s_waitcnt lgkmcnt(0)
	v_mov_b32_e32 v1, v0
	v_mov_b64_e32 v[2:3], 0
	v_mov_b64_e32 v[4:5], 0
	v_mov_b64_e32 v[6:7], 0
	v_mov_b64_e32 v[16:17], 0
	v_mov_b64_e32 v[18:19], 0
	v_mov_b64_e32 v[20:21], 0
	v_mov_b64_e32 v[22:23], 0
	v_mov_b64_e32 v[32:33], 0
	v_mov_b64_e32 v[34:35], 0
	v_mov_b64_e32 v[36:37], 0
	v_mov_b64_e32 v[38:39], 0
	v_mov_b64_e32 v[48:49], 0
	v_mov_b64_e32 v[50:51], 0
	v_mov_b64_e32 v[52:53], 0
	v_mov_b64_e32 v[54:55], 0
	v_mov_b64_e32 v[8:9], 0
	v_mov_b64_e32 v[10:11], 0
	v_mov_b64_e32 v[12:13], 0
	v_mov_b64_e32 v[14:15], 0
	v_mov_b64_e32 v[24:25], 0
	v_mov_b64_e32 v[26:27], 0
	v_mov_b64_e32 v[28:29], 0
	v_mov_b64_e32 v[30:31], 0
	v_mov_b64_e32 v[40:41], 0
	v_mov_b64_e32 v[42:43], 0
	v_mov_b64_e32 v[44:45], 0
	v_mov_b64_e32 v[46:47], 0
	v_mov_b64_e32 v[56:57], 0
	v_mov_b64_e32 v[58:59], 0
	v_mov_b64_e32 v[60:61], 0
	v_mov_b64_e32 v[62:63], 0
	v_mov_b64_e32 v[64:65], 0
	v_mov_b64_e32 v[66:67], 0
	v_mov_b64_e32 v[68:69], 0
	v_mov_b64_e32 v[70:71], 0
	v_mov_b64_e32 v[80:81], 0
	v_mov_b64_e32 v[82:83], 0
	v_mov_b64_e32 v[84:85], 0
	v_mov_b64_e32 v[86:87], 0
	v_mov_b64_e32 v[96:97], 0
	v_mov_b64_e32 v[98:99], 0
	v_mov_b64_e32 v[100:101], 0
	v_mov_b64_e32 v[102:103], 0
	v_mov_b64_e32 v[112:113], 0
	v_mov_b64_e32 v[114:115], 0
	v_mov_b64_e32 v[116:117], 0
	v_mov_b64_e32 v[118:119], 0
	v_mov_b64_e32 v[72:73], 0
	v_mov_b64_e32 v[74:75], 0
	v_mov_b64_e32 v[76:77], 0
	v_mov_b64_e32 v[78:79], 0
	v_mov_b64_e32 v[88:89], 0
	v_mov_b64_e32 v[90:91], 0
	v_mov_b64_e32 v[92:93], 0
	v_mov_b64_e32 v[94:95], 0
	v_mov_b64_e32 v[104:105], 0
	v_mov_b64_e32 v[106:107], 0
	v_mov_b64_e32 v[108:109], 0
	v_mov_b64_e32 v[110:111], 0
	v_mov_b64_e32 v[120:121], 0
	v_mov_b64_e32 v[122:123], 0
	v_mov_b64_e32 v[124:125], 0
	v_mov_b64_e32 v[126:127], 0

; template <class Epi, class Sched, bool ALIGN_EPI = false, bool SP2 = false>
; __device__ __forceinline__ void gemm_phase(PG8_LAS unsigned char* lds, const Gemm g, const Sched& S, const Epi& E) {
;     ...
; #pragma unroll
;         for (int a = 0; a < 2; ++a)
; #pragma unroll
;             for (int b = 0; b < 2; ++b)
; #pragma unroll
;                 for (int m = 0; m < 4; ++m)
; #pragma unroll
;                     for (int n = 0; n < 2; ++n) acc[a][b][m][n] = (f32x4){0.f, 0.f, 0.f, 0.f};
.LBB0_373:
	s_ashr_i32 s31, s30, 31
	s_lshl_b64 s[34:35], s[30:31], 19
	v_readlane_b32 s36, v235, 31
	v_readlane_b32 s37, v235, 32
	s_add_u32 s34, s36, s34
	s_addc_u32 s35, s37, s35
	s_and_b64 s[36:37], s[6:7], exec
	s_cselect_b32 s1, s35, s3
	s_cselect_b32 s25, s34, s2
	s_ashr_i32 s29, s28, 31
	s_lshl_b64 s[36:37], s[28:29], 19
	s_add_u32 s36, s10, s36
	s_addc_u32 s37, s11, s37
	s_and_b64 s[40:41], s[6:7], exec
	s_cselect_b32 s29, s37, s39
	s_cselect_b32 s31, s36, s38
	s_add_u32 s2, s2, 0x40080
	s_addc_u32 s3, s3, 0
	s_add_u32 s58, s38, 0x100
	v_mov_b32_e32 v0, 0
	s_addc_u32 s59, s39, 0
	s_mov_b32 s60, -2
	v_mov_b32_e32 v1, v0
	v_mov_b64_e32 v[2:3], 0
	v_mov_b64_e32 v[4:5], 0
	v_mov_b64_e32 v[6:7], 0
	v_mov_b64_e32 v[16:17], 0
	v_mov_b64_e32 v[18:19], 0
	v_mov_b64_e32 v[20:21], 0
	v_mov_b64_e32 v[22:23], 0
	v_mov_b64_e32 v[32:33], 0
	v_mov_b64_e32 v[34:35], 0
	v_mov_b64_e32 v[36:37], 0
	v_mov_b64_e32 v[38:39], 0
	v_mov_b64_e32 v[48:49], 0
	v_mov_b64_e32 v[50:51], 0
	v_mov_b64_e32 v[52:53], 0
	v_mov_b64_e32 v[54:55], 0
	v_mov_b64_e32 v[8:9], 0
	v_mov_b64_e32 v[10:11], 0
	v_mov_b64_e32 v[12:13], 0
	v_mov_b64_e32 v[14:15], 0
	v_mov_b64_e32 v[24:25], 0
	v_mov_b64_e32 v[26:27], 0
	v_mov_b64_e32 v[28:29], 0
	v_mov_b64_e32 v[30:31], 0
	v_mov_b64_e32 v[40:41], 0
	v_mov_b64_e32 v[42:43], 0
	v_mov_b64_e32 v[44:45], 0
	v_mov_b64_e32 v[46:47], 0
	v_mov_b64_e32 v[56:57], 0
	v_mov_b64_e32 v[58:59], 0
	v_mov_b64_e32 v[60:61], 0
	v_mov_b64_e32 v[62:63], 0
	v_mov_b64_e32 v[64:65], 0
	v_mov_b64_e32 v[66:67], 0
	v_mov_b64_e32 v[68:69], 0
	v_mov_b64_e32 v[70:71], 0
	v_mov_b64_e32 v[80:81], 0
	v_mov_b64_e32 v[82:83], 0
	v_mov_b64_e32 v[84:85], 0
	v_mov_b64_e32 v[86:87], 0
	v_mov_b64_e32 v[96:97], 0
	v_mov_b64_e32 v[98:99], 0
	v_mov_b64_e32 v[100:101], 0
	v_mov_b64_e32 v[102:103], 0
	v_mov_b64_e32 v[112:113], 0
	v_mov_b64_e32 v[114:115], 0
	v_mov_b64_e32 v[116:117], 0
	v_mov_b64_e32 v[118:119], 0
	v_mov_b64_e32 v[72:73], 0
	v_mov_b64_e32 v[74:75], 0
	v_mov_b64_e32 v[76:77], 0
	v_mov_b64_e32 v[78:79], 0
	v_mov_b64_e32 v[88:89], 0
	v_mov_b64_e32 v[90:91], 0
	v_mov_b64_e32 v[92:93], 0
	v_mov_b64_e32 v[94:95], 0
	v_mov_b64_e32 v[104:105], 0
	v_mov_b64_e32 v[106:107], 0
	v_mov_b64_e32 v[108:109], 0
	v_mov_b64_e32 v[110:111], 0
	v_mov_b64_e32 v[120:121], 0
	v_mov_b64_e32 v[122:123], 0
	v_mov_b64_e32 v[124:125], 0
	v_mov_b64_e32 v[126:127], 0

; template <class Epi, class Sched, bool ALIGN_EPI = false, bool SP2 = false>
; __device__ __forceinline__ void gemm_phase(PG8_LAS unsigned char* lds, const Gemm g, const Sched& S, const Epi& E) {
;     ...
; #pragma unroll
;         for (int a = 0; a < 2; ++a)
; #pragma unroll
;             for (int b = 0; b < 2; ++b)
; #pragma unroll
;                 for (int m = 0; m < 4; ++m)
; #pragma unroll
;                     for (int n = 0; n < 2; ++n) acc[a][b][m][n] = (f32x4){0.f, 0.f, 0.f, 0.f};
.LBB0_697:
	s_ashr_i32 s17, s16, 31
	s_lshl_b64 s[18:19], s[16:17], 19
	v_readlane_b32 s48, v235, 2
	v_readlane_b32 s49, v235, 3
	s_add_u32 s18, s48, s18
	s_addc_u32 s19, s49, s19
	s_and_b64 s[20:21], s[6:7], exec
	s_cselect_b32 s17, s19, s27
	s_cselect_b32 s23, s18, s26
	s_ashr_i32 s15, s14, 31
	s_lshl_b64 s[20:21], s[14:15], 19
	s_add_u32 s20, s33, s20
	s_addc_u32 s21, s34, s21
	s_and_b64 s[30:31], s[6:7], exec
	s_cselect_b32 s15, s21, s29
	s_cselect_b32 s47, s20, s28
	s_add_u32 s26, s26, 0x40080
	s_addc_u32 s27, s27, 0
	v_readlane_b32 s50, v235, 4
	s_add_u32 s48, s28, 0x100
	v_mov_b32_e32 v0, 0
	s_addc_u32 s49, s29, 0
	s_mov_b32 s50, -2
	s_waitcnt lgkmcnt(0)
	v_mov_b32_e32 v1, v0
	v_mov_b64_e32 v[2:3], 0
	v_mov_b64_e32 v[4:5], 0
	v_mov_b64_e32 v[6:7], 0
	v_mov_b64_e32 v[16:17], 0
	v_mov_b64_e32 v[18:19], 0
	v_mov_b64_e32 v[20:21], 0
	v_mov_b64_e32 v[22:23], 0
	v_mov_b64_e32 v[32:33], 0
	v_mov_b64_e32 v[34:35], 0
	v_mov_b64_e32 v[36:37], 0
	v_mov_b64_e32 v[38:39], 0
	v_mov_b64_e32 v[48:49], 0
	v_mov_b64_e32 v[50:51], 0
	v_mov_b64_e32 v[52:53], 0
	v_mov_b64_e32 v[54:55], 0
	v_mov_b64_e32 v[8:9], 0
	v_mov_b64_e32 v[10:11], 0
	v_mov_b64_e32 v[12:13], 0
	v_mov_b64_e32 v[14:15], 0
	v_mov_b64_e32 v[24:25], 0
	v_mov_b64_e32 v[26:27], 0
	v_mov_b64_e32 v[28:29], 0
	v_mov_b64_e32 v[30:31], 0
	v_mov_b64_e32 v[40:41], 0
	v_mov_b64_e32 v[42:43], 0
	v_mov_b64_e32 v[44:45], 0
	v_mov_b64_e32 v[46:47], 0
	v_mov_b64_e32 v[56:57], 0
	v_mov_b64_e32 v[58:59], 0
	v_mov_b64_e32 v[60:61], 0
	v_mov_b64_e32 v[62:63], 0
	v_mov_b64_e32 v[64:65], 0
	v_mov_b64_e32 v[66:67], 0
	v_mov_b64_e32 v[68:69], 0
	v_mov_b64_e32 v[70:71], 0
	v_mov_b64_e32 v[80:81], 0
	v_mov_b64_e32 v[82:83], 0
	v_mov_b64_e32 v[84:85], 0
	v_mov_b64_e32 v[86:87], 0
	v_mov_b64_e32 v[96:97], 0
	v_mov_b64_e32 v[98:99], 0
	v_mov_b64_e32 v[100:101], 0
	v_mov_b64_e32 v[102:103], 0
	v_mov_b64_e32 v[112:113], 0
	v_mov_b64_e32 v[114:115], 0
	v_mov_b64_e32 v[116:117], 0
	v_mov_b64_e32 v[118:119], 0
	v_mov_b64_e32 v[72:73], 0
	v_mov_b64_e32 v[74:75], 0
	v_mov_b64_e32 v[76:77], 0
	v_mov_b64_e32 v[78:79], 0
	v_mov_b64_e32 v[88:89], 0
	v_mov_b64_e32 v[90:91], 0
	v_mov_b64_e32 v[92:93], 0
	v_mov_b64_e32 v[94:95], 0
	v_mov_b64_e32 v[104:105], 0
	v_mov_b64_e32 v[106:107], 0
	v_mov_b64_e32 v[108:109], 0
	v_mov_b64_e32 v[110:111], 0
	v_mov_b64_e32 v[120:121], 0
	v_mov_b64_e32 v[122:123], 0
	v_mov_b64_e32 v[124:125], 0
	v_mov_b64_e32 v[126:127], 0
	v_readlane_b32 s51, v235, 5

; template <class Epi, class Sched, bool ALIGN_EPI = false, bool SP2 = false>
; __device__ __forceinline__ void gemm_phase(PG8_LAS unsigned char* lds, const Gemm g, const Sched& S, const Epi& E) {
;     ...
; #pragma unroll
;         for (int a = 0; a < 2; ++a)
; #pragma unroll
;             for (int b = 0; b < 2; ++b)
; #pragma unroll
;                 for (int m = 0; m < 4; ++m)
; #pragma unroll
;                     for (int n = 0; n < 2; ++n) acc[a][b][m][n] = (f32x4){0.f, 0.f, 0.f, 0.f};
.LBB0_861:
	s_add_u32 s49, s24, 0x100
	v_mov_b32_e32 v0, 0
	s_addc_u32 s50, s25, 0
	s_mov_b32 s51, -2
	v_mov_b32_e32 v1, v0
	v_mov_b64_e32 v[2:3], 0
	v_mov_b64_e32 v[4:5], 0
	v_mov_b64_e32 v[6:7], 0
	v_mov_b64_e32 v[16:17], 0
	v_mov_b64_e32 v[18:19], 0
	v_mov_b64_e32 v[20:21], 0
	v_mov_b64_e32 v[22:23], 0
	v_mov_b64_e32 v[32:33], 0
	v_mov_b64_e32 v[34:35], 0
	v_mov_b64_e32 v[36:37], 0
	v_mov_b64_e32 v[38:39], 0
	v_mov_b64_e32 v[48:49], 0
	v_mov_b64_e32 v[50:51], 0
	v_mov_b64_e32 v[52:53], 0
	v_mov_b64_e32 v[54:55], 0
	v_mov_b64_e32 v[8:9], 0
	v_mov_b64_e32 v[10:11], 0
	v_mov_b64_e32 v[12:13], 0
	v_mov_b64_e32 v[14:15], 0
	v_mov_b64_e32 v[24:25], 0
	v_mov_b64_e32 v[26:27], 0
	v_mov_b64_e32 v[28:29], 0
	v_mov_b64_e32 v[30:31], 0
	v_mov_b64_e32 v[40:41], 0
	v_mov_b64_e32 v[42:43], 0
	v_mov_b64_e32 v[44:45], 0
	v_mov_b64_e32 v[46:47], 0
	v_mov_b64_e32 v[56:57], 0
	v_mov_b64_e32 v[58:59], 0
	v_mov_b64_e32 v[60:61], 0
	v_mov_b64_e32 v[62:63], 0
	v_mov_b64_e32 v[64:65], 0
	v_mov_b64_e32 v[66:67], 0
	v_mov_b64_e32 v[68:69], 0
	v_mov_b64_e32 v[70:71], 0
	v_mov_b64_e32 v[80:81], 0
	v_mov_b64_e32 v[82:83], 0
	v_mov_b64_e32 v[84:85], 0
	v_mov_b64_e32 v[86:87], 0
	v_mov_b64_e32 v[96:97], 0
	v_mov_b64_e32 v[98:99], 0
	v_mov_b64_e32 v[100:101], 0
	v_mov_b64_e32 v[102:103], 0
	v_mov_b64_e32 v[112:113], 0
	v_mov_b64_e32 v[114:115], 0
	v_mov_b64_e32 v[116:117], 0
	v_mov_b64_e32 v[118:119], 0
	v_mov_b64_e32 v[72:73], 0
	v_mov_b64_e32 v[74:75], 0
	v_mov_b64_e32 v[76:77], 0
	v_mov_b64_e32 v[78:79], 0
	v_mov_b64_e32 v[88:89], 0
	v_mov_b64_e32 v[90:91], 0
	v_mov_b64_e32 v[92:93], 0
	v_mov_b64_e32 v[94:95], 0
	v_mov_b64_e32 v[104:105], 0
	v_mov_b64_e32 v[106:107], 0
	v_mov_b64_e32 v[108:109], 0
	v_mov_b64_e32 v[110:111], 0
	v_mov_b64_e32 v[120:121], 0
	v_mov_b64_e32 v[122:123], 0
	v_mov_b64_e32 v[124:125], 0
	v_mov_b64_e32 v[126:127], 0
